# attention epilogue: 64 global_store_short per lane replaced by per-wave LDS transpose + 8 global_store_dwordx4 per lane
# speedup vs baseline: 1.0071x; 1.0071x over previous
; __device__ __forceinline__ int crow(int r, int hi) { return (r & 3) + 8 * (r >> 2) + 4 * hi; }
; __device__ __forceinline__ unsigned cvtpk(float lo, float hi) { f32x2 v = {lo, hi}; bf16x2_t b = __builtin_convertvector(v, bf16x2_t); return __builtin_bit_cast(unsigned, b); }
; template <int MODE, int SD> ...
;     ...
;   if (hi == 0) li_l[r32] = l_reg; asm volatile("s_waitcnt lgkmcnt(0)" ::: "memory");
;   float rli[16];
; #pragma unroll
;   for (int r = 0; r < 16; ++r) rli[r] = __builtin_amdgcn_rcpf(li_l[crow(r, hi)]);
;   bf16_t* Ow = Ob + (long)(wid * QBLK) * LDO;
; #pragma unroll
;   for (int r = 0; r < 16; ++r) { const int orow = crow(r, hi);
; #pragma unroll
;     for (int d0 = 0; d0 < 4; ++d0) Ow[(long)orow * LDO + d0 * 32 + r32] = (bf16_t)(cvtpk(o[d0][r] * rli[r], 0.f) & 0xffffu); }
.LBB0_452:
	s_or_b64 exec, exec, s[18:19]
	v_lshl_add_u64 v[66:67], v[74:75], 0, v[0:1]
	v_lshrrev_b32_e32 v72, 6, v190
	v_lshlrev_b32_e32 v72, 11, v72
	v_add_u32_e32 v72, 0x20000, v72
	v_and_b32_e32 v73, 63, v190
	v_lshl_add_u32 v73, v73, 4, v72
	v_lshrrev_b32_e32 v74, 3, v190
	v_and_b32_e32 v74, 4, v74
	v_lshl_add_u32 v72, v74, 6, v72
	v_and_b32_e32 v75, 31, v190
	v_lshl_add_u32 v72, v75, 1, v72
	v_lshlrev_b32_e32 v74, 12, v74
	v_lshl_add_u32 v74, v75, 1, v74
	v_bfe_u32 v75, v190, 2, 4
	v_lshlrev_b32_e32 v75, 12, v75
	v_sub_u32_e32 v74, v75, v74
	v_and_b32_e32 v75, 3, v190
	v_lshl_add_u32 v74, v75, 4, v74
	v_ashrrev_i32_e32 v75, 31, v74
	v_lshl_add_u64 v[68:69], v[66:67], 0, v[74:75]
	s_mov_b64 s[8:9], 0x10000
	v_lshl_add_u64 v[70:71], v[68:69], 0, s[8:9]
	v_mul_f32_e32 v108, v50, v91
	v_mul_f32_e32 v109, v51, v90
	v_cvt_pk_bf16_f32 v110, v108, v109
	ds_write_b16 v72, v110
	ds_write_b16_d16_hi v72, v110 offset:64
	v_mul_f32_e32 v111, v52, v89
	v_mul_f32_e32 v112, v53, v88
	v_cvt_pk_bf16_f32 v113, v111, v112
	ds_write_b16 v72, v113 offset:128
	ds_write_b16_d16_hi v72, v113 offset:192
	v_mul_f32_e32 v114, v54, v87
	v_mul_f32_e32 v115, v55, v86
	v_cvt_pk_bf16_f32 v116, v114, v115
	ds_write_b16 v72, v116 offset:512
	ds_write_b16_d16_hi v72, v116 offset:576
	v_mul_f32_e32 v117, v56, v85
	v_mul_f32_e32 v118, v57, v84
	v_cvt_pk_bf16_f32 v119, v117, v118
	ds_write_b16 v72, v119 offset:640
	ds_write_b16_d16_hi v72, v119 offset:704
	v_mul_f32_e32 v108, v58, v83
	v_mul_f32_e32 v109, v59, v82
	v_cvt_pk_bf16_f32 v110, v108, v109
	ds_write_b16 v72, v110 offset:1024
	ds_write_b16_d16_hi v72, v110 offset:1088
	v_mul_f32_e32 v111, v60, v81
	v_mul_f32_e32 v112, v61, v80
	v_cvt_pk_bf16_f32 v113, v111, v112
	ds_write_b16 v72, v113 offset:1152
	ds_write_b16_d16_hi v72, v113 offset:1216
	v_mul_f32_e32 v114, v62, v79
	v_mul_f32_e32 v115, v63, v78
	v_cvt_pk_bf16_f32 v116, v114, v115
	ds_write_b16 v72, v116 offset:1536
	ds_write_b16_d16_hi v72, v116 offset:1600
	v_mul_f32_e32 v117, v64, v77
	v_mul_f32_e32 v118, v65, v76
	v_cvt_pk_bf16_f32 v119, v117, v118
	ds_write_b16 v72, v119 offset:1664
	ds_write_b16_d16_hi v72, v119 offset:1728
	ds_read_b128 v[92:95], v73
	ds_read_b128 v[96:99], v73 offset:1024
	v_mul_f32_e32 v108, v34, v91
	v_mul_f32_e32 v109, v35, v90
	v_cvt_pk_bf16_f32 v110, v108, v109
	ds_write_b16 v72, v110
	ds_write_b16_d16_hi v72, v110 offset:64
	v_mul_f32_e32 v111, v36, v89
	v_mul_f32_e32 v112, v37, v88
	v_cvt_pk_bf16_f32 v113, v111, v112
	ds_write_b16 v72, v113 offset:128
	ds_write_b16_d16_hi v72, v113 offset:192
	v_mul_f32_e32 v114, v38, v87
	v_mul_f32_e32 v115, v39, v86
	v_cvt_pk_bf16_f32 v116, v114, v115
	ds_write_b16 v72, v116 offset:512
	ds_write_b16_d16_hi v72, v116 offset:576
	v_mul_f32_e32 v117, v40, v85
	v_mul_f32_e32 v118, v41, v84
	v_cvt_pk_bf16_f32 v119, v117, v118
	ds_write_b16 v72, v119 offset:640
	ds_write_b16_d16_hi v72, v119 offset:704
	v_mul_f32_e32 v108, v42, v83
	v_mul_f32_e32 v109, v43, v82
	v_cvt_pk_bf16_f32 v110, v108, v109
	ds_write_b16 v72, v110 offset:1024
	ds_write_b16_d16_hi v72, v110 offset:1088
	v_mul_f32_e32 v111, v44, v81
	v_mul_f32_e32 v112, v45, v80
	v_cvt_pk_bf16_f32 v113, v111, v112
	ds_write_b16 v72, v113 offset:1152
	ds_write_b16_d16_hi v72, v113 offset:1216
	v_mul_f32_e32 v114, v46, v79
	v_mul_f32_e32 v115, v47, v78
	v_cvt_pk_bf16_f32 v116, v114, v115
	ds_write_b16 v72, v116 offset:1536
	ds_write_b16_d16_hi v72, v116 offset:1600
	v_mul_f32_e32 v117, v48, v77
	v_mul_f32_e32 v118, v49, v76
	v_cvt_pk_bf16_f32 v119, v117, v118
	ds_write_b16 v72, v119 offset:1664
	ds_write_b16_d16_hi v72, v119 offset:1728
	s_waitcnt lgkmcnt(15)
; __device__ __forceinline__ int crow(int r, int hi) { return (r & 3) + 8 * (r >> 2) + 4 * hi; }
; __device__ __forceinline__ unsigned cvtpk(float lo, float hi) { f32x2 v = {lo, hi}; bf16x2_t b = __builtin_convertvector(v, bf16x2_t); return __builtin_bit_cast(unsigned, b); }
; template <int MODE, int SD> ...
;     ...
;   bf16_t* Ow = Ob + (long)(wid * QBLK) * LDO;
; #pragma unroll
;   for (int r = 0; r < 16; ++r) { const int orow = crow(r, hi);
; #pragma unroll
;     for (int d0 = 0; d0 < 4; ++d0) Ow[(long)orow * LDO + d0 * 32 + r32] = (bf16_t)(cvtpk(o[d0][r] * rli[r], 0.f) & 0xffffu); }
;   if (ATT_PRIO) __builtin_amdgcn_s_setprio(0);
	global_store_dwordx4 v[68:69], v[92:95], off
	global_store_dwordx4 v[70:71], v[96:99], off
	ds_read_b128 v[100:103], v73
	ds_read_b128 v[104:107], v73 offset:1024
	v_mul_f32_e32 v108, v18, v91
	v_mul_f32_e32 v109, v19, v90
	v_cvt_pk_bf16_f32 v110, v108, v109
	ds_write_b16 v72, v110
	ds_write_b16_d16_hi v72, v110 offset:64
	v_mul_f32_e32 v111, v20, v89
	v_mul_f32_e32 v112, v21, v88
	v_cvt_pk_bf16_f32 v113, v111, v112
	ds_write_b16 v72, v113 offset:128
	ds_write_b16_d16_hi v72, v113 offset:192
	v_mul_f32_e32 v114, v22, v87
	v_mul_f32_e32 v115, v23, v86
	v_cvt_pk_bf16_f32 v116, v114, v115
	ds_write_b16 v72, v116 offset:512
	ds_write_b16_d16_hi v72, v116 offset:576
	v_mul_f32_e32 v117, v24, v85
	v_mul_f32_e32 v118, v25, v84
	v_cvt_pk_bf16_f32 v119, v117, v118
	ds_write_b16 v72, v119 offset:640
	ds_write_b16_d16_hi v72, v119 offset:704
	v_mul_f32_e32 v108, v26, v83
	v_mul_f32_e32 v109, v27, v82
	v_cvt_pk_bf16_f32 v110, v108, v109
	ds_write_b16 v72, v110 offset:1024
	ds_write_b16_d16_hi v72, v110 offset:1088
	v_mul_f32_e32 v111, v28, v81
	v_mul_f32_e32 v112, v29, v80
	v_cvt_pk_bf16_f32 v113, v111, v112
	ds_write_b16 v72, v113 offset:1152
	ds_write_b16_d16_hi v72, v113 offset:1216
	v_mul_f32_e32 v114, v30, v79
	v_mul_f32_e32 v115, v31, v78
	v_cvt_pk_bf16_f32 v116, v114, v115
	ds_write_b16 v72, v116 offset:1536
	ds_write_b16_d16_hi v72, v116 offset:1600
	v_mul_f32_e32 v117, v32, v77
	v_mul_f32_e32 v118, v33, v76
	v_cvt_pk_bf16_f32 v119, v117, v118
	ds_write_b16 v72, v119 offset:1664
	ds_write_b16_d16_hi v72, v119 offset:1728
	s_waitcnt lgkmcnt(15)
	global_store_dwordx4 v[68:69], v[100:103], off offset:64
	global_store_dwordx4 v[70:71], v[104:107], off offset:64
	ds_read_b128 v[92:95], v73
	ds_read_b128 v[96:99], v73 offset:1024
	v_mul_f32_e32 v108, v2, v91
	v_mul_f32_e32 v109, v3, v90
	v_cvt_pk_bf16_f32 v110, v108, v109
	ds_write_b16 v72, v110
	ds_write_b16_d16_hi v72, v110 offset:64
	v_mul_f32_e32 v111, v4, v89
	v_mul_f32_e32 v112, v5, v88
	v_cvt_pk_bf16_f32 v113, v111, v112
	ds_write_b16 v72, v113 offset:128
	ds_write_b16_d16_hi v72, v113 offset:192
	v_mul_f32_e32 v114, v6, v87
	v_mul_f32_e32 v115, v7, v86
	v_cvt_pk_bf16_f32 v116, v114, v115
	ds_write_b16 v72, v116 offset:512
	ds_write_b16_d16_hi v72, v116 offset:576
	v_mul_f32_e32 v117, v8, v85
	v_mul_f32_e32 v118, v9, v84
	v_cvt_pk_bf16_f32 v119, v117, v118
	ds_write_b16 v72, v119 offset:640
	ds_write_b16_d16_hi v72, v119 offset:704
	v_mul_f32_e32 v108, v10, v83
	v_mul_f32_e32 v109, v11, v82
	v_cvt_pk_bf16_f32 v110, v108, v109
	ds_write_b16 v72, v110 offset:1024
	ds_write_b16_d16_hi v72, v110 offset:1088
	v_mul_f32_e32 v111, v12, v81
	v_mul_f32_e32 v112, v13, v80
	v_cvt_pk_bf16_f32 v113, v111, v112
	ds_write_b16 v72, v113 offset:1152
	ds_write_b16_d16_hi v72, v113 offset:1216
	v_mul_f32_e32 v114, v14, v79
	v_mul_f32_e32 v115, v15, v78
	v_cvt_pk_bf16_f32 v116, v114, v115
	ds_write_b16 v72, v116 offset:1536
	ds_write_b16_d16_hi v72, v116 offset:1600
	v_mul_f32_e32 v117, v16, v77
	v_mul_f32_e32 v118, v17, v76
	v_cvt_pk_bf16_f32 v119, v117, v118
	ds_write_b16 v72, v119 offset:1664
	ds_write_b16_d16_hi v72, v119 offset:1728
	s_waitcnt lgkmcnt(15)
	global_store_dwordx4 v[68:69], v[92:95], off offset:128
	global_store_dwordx4 v[70:71], v[96:99], off offset:128
	ds_read_b128 v[100:103], v73
	ds_read_b128 v[104:107], v73 offset:1024
	s_waitcnt lgkmcnt(0)
	global_store_dwordx4 v[68:69], v[100:103], off offset:192
	global_store_dwordx4 v[70:71], v[104:107], off offset:192
	s_setprio 0
	s_xor_b64 s[8:9], exec, -1
